# non-last workgroups poll the global barrier generation word directly instead of the per-XCD relay word
# speedup vs baseline: 1.0111x; 1.0042x over previous
; __device__ __forceinline__ unsigned xb_ld(unsigned* p)              { return __hip_atomic_load(p, __ATOMIC_RELAXED, __HIP_MEMORY_SCOPE_AGENT); }
; __device__ __forceinline__ unsigned xb_add(unsigned* p, unsigned v) { return __hip_atomic_fetch_add(p, v, __ATOMIC_RELAXED, __HIP_MEMORY_SCOPE_AGENT); }
; #define XB_SPIN(cond, bar) do { unsigned _sp = 0; while (cond) { __builtin_amdgcn_s_sleep(1); \
;     if ((++_sp & 255u) == 0u) { if (xb_ld(&(bar)[XB_TMO])) break; if (_sp > XB_SPIN_CAP) { atomicAdd(&(bar)[XB_TMO], 1u); break; } } } } while (0)
; __device__ __forceinline__ void xcd_barrier(const XcdBarrier& b, int wv) {
;     ...
;         const unsigned old = xb_add(&bar[XB_XSUB(bx)], 1u);
;         const unsigned gen = old / nloc;
;         if (old + 1u == (gen + 1u) * nloc) {
;             __builtin_amdgcn_fence(__ATOMIC_RELEASE, "agent");
;             asm volatile("s_waitcnt vmcnt(0)" ::: "memory");
;             const unsigned og = xb_add(&bar[XB_TOP], 1u);
;             const unsigned tg = og / nx;
;             if (og + 1u == (tg + 1u) * nx) xb_add(&bar[XB_TOPGEN], 1u);
;             else XB_SPIN(xb_ld(&bar[XB_TOPGEN]) == tg, bar);
;             __builtin_amdgcn_fence(__ATOMIC_ACQUIRE, "agent");
;             xb_add(&bar[XB_XGEN(bx)], 1u);
;             asm volatile("s_waitcnt vmcnt(0)" ::: "memory");
;         } else {
;             XB_SPIN(xb_ld(&bar[XB_XGEN(bx)]) == gen, bar);
;             __builtin_amdgcn_fence(__ATOMIC_ACQUIRE, "agent");
;             asm volatile("s_waitcnt vmcnt(0)" ::: "memory");
.LBB0_142:
	s_or_b64 exec, exec, s[6:7]
	v_cvt_f32_u32_e32 v4, v2
	s_waitcnt vmcnt(0)
	v_readfirstlane_b32 s4, v3
	v_sub_u32_e32 v3, 0, v2
	v_rcp_iflag_f32_e32 v4, v4
	v_add_u32_e32 v5, s4, v1
	v_mul_f32_e32 v4, 0x4f7ffffe, v4
	v_cvt_u32_f32_e32 v4, v4
	v_mul_lo_u32 v1, v3, v4
	v_mul_hi_u32 v1, v4, v1
	v_add_u32_e32 v1, v4, v1
	v_mul_hi_u32 v1, v5, v1
	v_mul_lo_u32 v3, v1, v2
	v_sub_u32_e32 v3, v5, v3
	v_add_u32_e32 v4, 1, v1
	v_cmp_ge_u32_e32 vcc, v3, v2
	s_nop 1
	v_cndmask_b32_e32 v1, v1, v4, vcc
	v_sub_u32_e32 v4, v3, v2
	v_cndmask_b32_e32 v3, v3, v4, vcc
	v_add_u32_e32 v4, 1, v1
	v_cmp_ge_u32_e32 vcc, v3, v2
	v_add_u32_e32 v3, 1, v5
	s_nop 0
	v_cndmask_b32_e32 v1, v1, v4, vcc
	v_mul_lo_u32 v4, v2, v1
	v_add_u32_e32 v2, v4, v2
	v_cmp_ne_u32_e32 vcc, v3, v2
	s_and_saveexec_b64 s[4:5], vcc
	s_xor_b64 s[4:5], exec, s[4:5]
	s_cbranch_execz .LBB0_156
	s_movk_i32 s6, 0xd40
	s_mov_b32 s7, 0
	s_lshl_b64 s[6:7], s[6:7], 2
	s_add_u32 s10, s82, s6
	s_addc_u32 s11, s83, s7
	s_waitcnt lgkmcnt(0)
	v_mov_b32_e32 v0, 0
	global_load_dword v2, v0, s[10:11] sc1
	s_waitcnt vmcnt(0)
	v_cmp_eq_u32_e32 vcc, v2, v1
	s_and_saveexec_b64 s[6:7], vcc
	s_cbranch_execz .LBB0_155
	s_add_u32 s8, s30, 0x3e9200
	s_addc_u32 s9, s31, 0
	s_mov_b32 s36, 1
	s_mov_b64 s[12:13], 0
	s_branch .LBB0_146

; __device__ __forceinline__ unsigned xb_ld(unsigned* p)              { return __hip_atomic_load(p, __ATOMIC_RELAXED, __HIP_MEMORY_SCOPE_AGENT); }
; __device__ __forceinline__ unsigned xb_add(unsigned* p, unsigned v) { return __hip_atomic_fetch_add(p, v, __ATOMIC_RELAXED, __HIP_MEMORY_SCOPE_AGENT); }
; #define XB_SPIN(cond, bar) do { unsigned _sp = 0; while (cond) { __builtin_amdgcn_s_sleep(1); \
;     if ((++_sp & 255u) == 0u) { if (xb_ld(&(bar)[XB_TMO])) break; if (_sp > XB_SPIN_CAP) { atomicAdd(&(bar)[XB_TMO], 1u); break; } } } } while (0)
; __device__ __forceinline__ void xcd_barrier(const XcdBarrier& b, int wv) {
;     ...
;         const unsigned old = xb_add(&bar[XB_XSUB(bx)], 1u);
;         const unsigned gen = old / nloc;
;         if (old + 1u == (gen + 1u) * nloc) {
;             __builtin_amdgcn_fence(__ATOMIC_RELEASE, "agent");
;             asm volatile("s_waitcnt vmcnt(0)" ::: "memory");
;             const unsigned og = xb_add(&bar[XB_TOP], 1u);
;             const unsigned tg = og / nx;
;             if (og + 1u == (tg + 1u) * nx) xb_add(&bar[XB_TOPGEN], 1u);
;             else XB_SPIN(xb_ld(&bar[XB_TOPGEN]) == tg, bar);
;             __builtin_amdgcn_fence(__ATOMIC_ACQUIRE, "agent");
;             xb_add(&bar[XB_XGEN(bx)], 1u);
;             asm volatile("s_waitcnt vmcnt(0)" ::: "memory");
;         } else {
;             XB_SPIN(xb_ld(&bar[XB_XGEN(bx)]) == gen, bar);
;             __builtin_amdgcn_fence(__ATOMIC_ACQUIRE, "agent");
;             asm volatile("s_waitcnt vmcnt(0)" ::: "memory");
.LBB0_243:
	s_or_b64 exec, exec, s[14:15]
	v_cvt_f32_u32_e32 v5, v3
	s_waitcnt vmcnt(0)
	v_readfirstlane_b32 s10, v4
	v_sub_u32_e32 v4, 0, v3
	v_rcp_iflag_f32_e32 v5, v5
	v_add_u32_e32 v6, s10, v1
	v_mul_f32_e32 v5, 0x4f7ffffe, v5
	v_cvt_u32_f32_e32 v5, v5
	v_mul_lo_u32 v1, v4, v5
	v_mul_hi_u32 v1, v5, v1
	v_add_u32_e32 v1, v5, v1
	v_mul_hi_u32 v1, v6, v1
	v_mul_lo_u32 v4, v1, v3
	v_sub_u32_e32 v4, v6, v4
	v_add_u32_e32 v5, 1, v1
	v_cmp_ge_u32_e32 vcc, v4, v3
	s_nop 1
	v_cndmask_b32_e32 v1, v1, v5, vcc
	v_sub_u32_e32 v5, v4, v3
	v_cndmask_b32_e32 v4, v4, v5, vcc
	v_add_u32_e32 v5, 1, v1
	v_cmp_ge_u32_e32 vcc, v4, v3
	v_add_u32_e32 v4, 1, v6
	s_nop 0
	v_cndmask_b32_e32 v1, v1, v5, vcc
	v_mul_lo_u32 v5, v3, v1
	v_add_u32_e32 v3, v5, v3
	v_cmp_ne_u32_e32 vcc, v4, v3
	s_and_saveexec_b64 s[10:11], vcc
	s_xor_b64 s[10:11], exec, s[10:11]
	s_cbranch_execz .LBB0_257
	s_movk_i32 s36, 0xd40
	s_lshl_b64 s[14:15], s[36:37], 2
	s_add_u32 s16, s82, s14
	s_addc_u32 s17, s83, s15
	s_waitcnt lgkmcnt(0)
	global_load_dword v2, v0, s[16:17] sc1
	s_waitcnt vmcnt(0)
	v_cmp_eq_u32_e32 vcc, v2, v1
	s_and_saveexec_b64 s[14:15], vcc
	s_cbranch_execz .LBB0_256
	s_mov_b32 s36, 1
	s_mov_b64 s[20:21], 0
	s_branch .LBB0_247

; __device__ __forceinline__ unsigned xb_ld(unsigned* p)              { return __hip_atomic_load(p, __ATOMIC_RELAXED, __HIP_MEMORY_SCOPE_AGENT); }
; __device__ __forceinline__ unsigned xb_add(unsigned* p, unsigned v) { return __hip_atomic_fetch_add(p, v, __ATOMIC_RELAXED, __HIP_MEMORY_SCOPE_AGENT); }
; #define XB_SPIN(cond, bar) do { unsigned _sp = 0; while (cond) { __builtin_amdgcn_s_sleep(1); \
;     if ((++_sp & 255u) == 0u) { if (xb_ld(&(bar)[XB_TMO])) break; if (_sp > XB_SPIN_CAP) { atomicAdd(&(bar)[XB_TMO], 1u); break; } } } } while (0)
; __device__ __forceinline__ void xcd_barrier(const XcdBarrier& b, int wv) {
;     ...
;         const unsigned old = xb_add(&bar[XB_XSUB(bx)], 1u);
;         const unsigned gen = old / nloc;
;         if (old + 1u == (gen + 1u) * nloc) {
;             __builtin_amdgcn_fence(__ATOMIC_RELEASE, "agent");
;             asm volatile("s_waitcnt vmcnt(0)" ::: "memory");
;             const unsigned og = xb_add(&bar[XB_TOP], 1u);
;             const unsigned tg = og / nx;
;             if (og + 1u == (tg + 1u) * nx) xb_add(&bar[XB_TOPGEN], 1u);
;             else XB_SPIN(xb_ld(&bar[XB_TOPGEN]) == tg, bar);
;             __builtin_amdgcn_fence(__ATOMIC_ACQUIRE, "agent");
;             xb_add(&bar[XB_XGEN(bx)], 1u);
;             asm volatile("s_waitcnt vmcnt(0)" ::: "memory");
;         } else {
;             XB_SPIN(xb_ld(&bar[XB_XGEN(bx)]) == gen, bar);
;             __builtin_amdgcn_fence(__ATOMIC_ACQUIRE, "agent");
;             asm volatile("s_waitcnt vmcnt(0)" ::: "memory");
.LBB0_351:
	s_or_b64 exec, exec, s[10:11]
	v_cvt_f32_u32_e32 v5, v3
	s_waitcnt vmcnt(0)
	v_readfirstlane_b32 s6, v4
	v_sub_u32_e32 v4, 0, v3
	v_rcp_iflag_f32_e32 v5, v5
	v_add_u32_e32 v6, s6, v1
	v_mul_f32_e32 v5, 0x4f7ffffe, v5
	v_cvt_u32_f32_e32 v5, v5
	v_mul_lo_u32 v1, v4, v5
	v_mul_hi_u32 v1, v5, v1
	v_add_u32_e32 v1, v5, v1
	v_mul_hi_u32 v1, v6, v1
	v_mul_lo_u32 v4, v1, v3
	v_sub_u32_e32 v4, v6, v4
	v_add_u32_e32 v5, 1, v1
	v_cmp_ge_u32_e32 vcc, v4, v3
	s_nop 1
	v_cndmask_b32_e32 v1, v1, v5, vcc
	v_sub_u32_e32 v5, v4, v3
	v_cndmask_b32_e32 v4, v4, v5, vcc
	v_add_u32_e32 v5, 1, v1
	v_cmp_ge_u32_e32 vcc, v4, v3
	v_add_u32_e32 v4, 1, v6
	s_nop 0
	v_cndmask_b32_e32 v1, v1, v5, vcc
	v_mul_lo_u32 v5, v3, v1
	v_add_u32_e32 v3, v5, v3
	v_cmp_ne_u32_e32 vcc, v4, v3
	s_and_saveexec_b64 s[6:7], vcc
	s_xor_b64 s[6:7], exec, s[6:7]
	s_cbranch_execz .LBB0_365
	s_movk_i32 s36, 0xd40
	s_lshl_b64 s[10:11], s[36:37], 2
	s_add_u32 s14, s82, s10
	s_addc_u32 s15, s83, s11
	s_waitcnt lgkmcnt(0)
	global_load_dword v2, v0, s[14:15] sc1
	s_waitcnt vmcnt(0)
	v_cmp_eq_u32_e32 vcc, v2, v1
	s_and_saveexec_b64 s[10:11], vcc
	s_cbranch_execz .LBB0_364
	s_mov_b32 s36, 1
	s_mov_b64 s[16:17], 0
	s_branch .LBB0_355

; __device__ __forceinline__ unsigned xb_ld(unsigned* p)              { return __hip_atomic_load(p, __ATOMIC_RELAXED, __HIP_MEMORY_SCOPE_AGENT); }
; __device__ __forceinline__ unsigned xb_add(unsigned* p, unsigned v) { return __hip_atomic_fetch_add(p, v, __ATOMIC_RELAXED, __HIP_MEMORY_SCOPE_AGENT); }
; #define XB_SPIN(cond, bar) do { unsigned _sp = 0; while (cond) { __builtin_amdgcn_s_sleep(1); \
;     if ((++_sp & 255u) == 0u) { if (xb_ld(&(bar)[XB_TMO])) break; if (_sp > XB_SPIN_CAP) { atomicAdd(&(bar)[XB_TMO], 1u); break; } } } } while (0)
; __device__ __forceinline__ void xcd_barrier(const XcdBarrier& b, int wv) {
;     ...
;         const unsigned old = xb_add(&bar[XB_XSUB(bx)], 1u);
;         const unsigned gen = old / nloc;
;         if (old + 1u == (gen + 1u) * nloc) {
;             __builtin_amdgcn_fence(__ATOMIC_RELEASE, "agent");
;             asm volatile("s_waitcnt vmcnt(0)" ::: "memory");
;             const unsigned og = xb_add(&bar[XB_TOP], 1u);
;             const unsigned tg = og / nx;
;             if (og + 1u == (tg + 1u) * nx) xb_add(&bar[XB_TOPGEN], 1u);
;             else XB_SPIN(xb_ld(&bar[XB_TOPGEN]) == tg, bar);
;             __builtin_amdgcn_fence(__ATOMIC_ACQUIRE, "agent");
;             xb_add(&bar[XB_XGEN(bx)], 1u);
;             asm volatile("s_waitcnt vmcnt(0)" ::: "memory");
;         } else {
;             XB_SPIN(xb_ld(&bar[XB_XGEN(bx)]) == gen, bar);
;             __builtin_amdgcn_fence(__ATOMIC_ACQUIRE, "agent");
;             asm volatile("s_waitcnt vmcnt(0)" ::: "memory");
.LBB0_525:
	s_or_b64 exec, exec, s[6:7]
	v_cvt_f32_u32_e32 v5, v3
	s_waitcnt vmcnt(0)
	v_readfirstlane_b32 s4, v4
	v_sub_u32_e32 v4, 0, v3
	v_rcp_iflag_f32_e32 v5, v5
	v_add_u32_e32 v6, s4, v1
	v_mul_f32_e32 v5, 0x4f7ffffe, v5
	v_cvt_u32_f32_e32 v5, v5
	v_mul_lo_u32 v1, v4, v5
	v_mul_hi_u32 v1, v5, v1
	v_add_u32_e32 v1, v5, v1
	v_mul_hi_u32 v1, v6, v1
	v_mul_lo_u32 v4, v1, v3
	v_sub_u32_e32 v4, v6, v4
	v_add_u32_e32 v5, 1, v1
	v_cmp_ge_u32_e32 vcc, v4, v3
	s_nop 1
	v_cndmask_b32_e32 v1, v1, v5, vcc
	v_sub_u32_e32 v5, v4, v3
	v_cndmask_b32_e32 v4, v4, v5, vcc
	v_add_u32_e32 v5, 1, v1
	v_cmp_ge_u32_e32 vcc, v4, v3
	v_add_u32_e32 v4, 1, v6
	s_nop 0
	v_cndmask_b32_e32 v1, v1, v5, vcc
	v_mul_lo_u32 v5, v3, v1
	v_add_u32_e32 v3, v5, v3
	v_cmp_ne_u32_e32 vcc, v4, v3
	s_and_saveexec_b64 s[4:5], vcc
	s_xor_b64 s[4:5], exec, s[4:5]
	s_cbranch_execz .LBB0_539
	s_movk_i32 s36, 0xd40
	s_lshl_b64 s[6:7], s[36:37], 2
	s_add_u32 s8, s82, s6
	s_addc_u32 s9, s83, s7
	s_waitcnt lgkmcnt(0)
	global_load_dword v2, v0, s[8:9] sc1
	s_waitcnt vmcnt(0)
	v_cmp_eq_u32_e32 vcc, v2, v1
	s_and_saveexec_b64 s[6:7], vcc
	s_cbranch_execz .LBB0_538
	s_mov_b32 s36, 1
	s_mov_b64 s[10:11], 0
	s_branch .LBB0_529

; __device__ __forceinline__ unsigned xb_ld(unsigned* p)              { return __hip_atomic_load(p, __ATOMIC_RELAXED, __HIP_MEMORY_SCOPE_AGENT); }
; __device__ __forceinline__ unsigned xb_add(unsigned* p, unsigned v) { return __hip_atomic_fetch_add(p, v, __ATOMIC_RELAXED, __HIP_MEMORY_SCOPE_AGENT); }
; #define XB_SPIN(cond, bar) do { unsigned _sp = 0; while (cond) { __builtin_amdgcn_s_sleep(1); \
;     if ((++_sp & 255u) == 0u) { if (xb_ld(&(bar)[XB_TMO])) break; if (_sp > XB_SPIN_CAP) { atomicAdd(&(bar)[XB_TMO], 1u); break; } } } } while (0)
; __device__ __forceinline__ void xcd_barrier(const XcdBarrier& b, int wv) {
;     ...
;         const unsigned old = xb_add(&bar[XB_XSUB(bx)], 1u);
;         const unsigned gen = old / nloc;
;         if (old + 1u == (gen + 1u) * nloc) {
;             __builtin_amdgcn_fence(__ATOMIC_RELEASE, "agent");
;             asm volatile("s_waitcnt vmcnt(0)" ::: "memory");
;             const unsigned og = xb_add(&bar[XB_TOP], 1u);
;             const unsigned tg = og / nx;
;             if (og + 1u == (tg + 1u) * nx) xb_add(&bar[XB_TOPGEN], 1u);
;             else XB_SPIN(xb_ld(&bar[XB_TOPGEN]) == tg, bar);
;             __builtin_amdgcn_fence(__ATOMIC_ACQUIRE, "agent");
;             xb_add(&bar[XB_XGEN(bx)], 1u);
;             asm volatile("s_waitcnt vmcnt(0)" ::: "memory");
;         } else {
;             XB_SPIN(xb_ld(&bar[XB_XGEN(bx)]) == gen, bar);
;             __builtin_amdgcn_fence(__ATOMIC_ACQUIRE, "agent");
;             asm volatile("s_waitcnt vmcnt(0)" ::: "memory");
.LBB0_764:
	s_or_b64 exec, exec, s[6:7]
	v_cvt_f32_u32_e32 v5, v3
	s_waitcnt vmcnt(0)
	v_readfirstlane_b32 s4, v4
	v_sub_u32_e32 v4, 0, v3
	v_rcp_iflag_f32_e32 v5, v5
	v_add_u32_e32 v6, s4, v1
	v_mul_f32_e32 v5, 0x4f7ffffe, v5
	v_cvt_u32_f32_e32 v5, v5
	v_mul_lo_u32 v1, v4, v5
	v_mul_hi_u32 v1, v5, v1
	v_add_u32_e32 v1, v5, v1
	v_mul_hi_u32 v1, v6, v1
	v_mul_lo_u32 v4, v1, v3
	v_sub_u32_e32 v4, v6, v4
	v_add_u32_e32 v5, 1, v1
	v_cmp_ge_u32_e32 vcc, v4, v3
	s_nop 1
	v_cndmask_b32_e32 v1, v1, v5, vcc
	v_sub_u32_e32 v5, v4, v3
	v_cndmask_b32_e32 v4, v4, v5, vcc
	v_add_u32_e32 v5, 1, v1
	v_cmp_ge_u32_e32 vcc, v4, v3
	v_add_u32_e32 v4, 1, v6
	s_nop 0
	v_cndmask_b32_e32 v1, v1, v5, vcc
	v_mul_lo_u32 v5, v3, v1
	v_add_u32_e32 v3, v5, v3
	v_cmp_ne_u32_e32 vcc, v4, v3
	s_and_saveexec_b64 s[4:5], vcc
	s_xor_b64 s[4:5], exec, s[4:5]
	s_cbranch_execz .LBB0_778
	s_movk_i32 s36, 0xd40
	s_lshl_b64 s[6:7], s[36:37], 2
	s_add_u32 s8, s82, s6
	s_addc_u32 s9, s83, s7
	s_waitcnt lgkmcnt(0)
	global_load_dword v2, v0, s[8:9] sc1
	s_waitcnt vmcnt(0)
	v_cmp_eq_u32_e32 vcc, v2, v1
	s_and_saveexec_b64 s[6:7], vcc
	s_cbranch_execz .LBB0_777
	s_mov_b32 s36, 1
	s_mov_b64 s[12:13], 0
	s_branch .LBB0_768

; __device__ __forceinline__ unsigned xb_ld(unsigned* p)              { return __hip_atomic_load(p, __ATOMIC_RELAXED, __HIP_MEMORY_SCOPE_AGENT); }
; __device__ __forceinline__ unsigned xb_add(unsigned* p, unsigned v) { return __hip_atomic_fetch_add(p, v, __ATOMIC_RELAXED, __HIP_MEMORY_SCOPE_AGENT); }
; #define XB_SPIN(cond, bar) do { unsigned _sp = 0; while (cond) { __builtin_amdgcn_s_sleep(1); \
;     if ((++_sp & 255u) == 0u) { if (xb_ld(&(bar)[XB_TMO])) break; if (_sp > XB_SPIN_CAP) { atomicAdd(&(bar)[XB_TMO], 1u); break; } } } } while (0)
; __device__ __forceinline__ void xcd_barrier(const XcdBarrier& b, int wv) {
;     ...
;         const unsigned old = xb_add(&bar[XB_XSUB(bx)], 1u);
;         const unsigned gen = old / nloc;
;         if (old + 1u == (gen + 1u) * nloc) {
;             __builtin_amdgcn_fence(__ATOMIC_RELEASE, "agent");
;             asm volatile("s_waitcnt vmcnt(0)" ::: "memory");
;             const unsigned og = xb_add(&bar[XB_TOP], 1u);
;             const unsigned tg = og / nx;
;             if (og + 1u == (tg + 1u) * nx) xb_add(&bar[XB_TOPGEN], 1u);
;             else XB_SPIN(xb_ld(&bar[XB_TOPGEN]) == tg, bar);
;             __builtin_amdgcn_fence(__ATOMIC_ACQUIRE, "agent");
;             xb_add(&bar[XB_XGEN(bx)], 1u);
;             asm volatile("s_waitcnt vmcnt(0)" ::: "memory");
;         } else {
;             XB_SPIN(xb_ld(&bar[XB_XGEN(bx)]) == gen, bar);
;             __builtin_amdgcn_fence(__ATOMIC_ACQUIRE, "agent");
;             asm volatile("s_waitcnt vmcnt(0)" ::: "memory");
.LBB0_818:
	s_or_b64 exec, exec, s[10:11]
	v_cvt_f32_u32_e32 v8, v6
	s_waitcnt vmcnt(0)
	v_readfirstlane_b32 s8, v7
	v_sub_u32_e32 v7, 0, v6
	v_rcp_iflag_f32_e32 v8, v8
	v_add_u32_e32 v9, s8, v5
	v_mul_f32_e32 v8, 0x4f7ffffe, v8
	v_cvt_u32_f32_e32 v8, v8
	v_mul_lo_u32 v5, v7, v8
	v_mul_hi_u32 v5, v8, v5
	v_add_u32_e32 v5, v8, v5
	v_mul_hi_u32 v5, v9, v5
	v_mul_lo_u32 v7, v5, v6
	v_sub_u32_e32 v7, v9, v7
	v_add_u32_e32 v8, 1, v5
	v_cmp_ge_u32_e32 vcc, v7, v6
	s_nop 1
	v_cndmask_b32_e32 v5, v5, v8, vcc
	v_sub_u32_e32 v8, v7, v6
	v_cndmask_b32_e32 v7, v7, v8, vcc
	v_add_u32_e32 v8, 1, v5
	v_cmp_ge_u32_e32 vcc, v7, v6
	v_add_u32_e32 v7, 1, v9
	s_nop 0
	v_cndmask_b32_e32 v5, v5, v8, vcc
	v_mul_lo_u32 v8, v6, v5
	v_add_u32_e32 v6, v8, v6
	v_cmp_ne_u32_e32 vcc, v7, v6
	s_and_saveexec_b64 s[8:9], vcc
	s_xor_b64 s[8:9], exec, s[8:9]
	s_cbranch_execz .LBB0_832
	s_movk_i32 s10, 0xd40
	s_mov_b32 s11, 0
	s_lshl_b64 s[10:11], s[10:11], 2
	s_add_u32 s12, s82, s10
	s_addc_u32 s13, s83, s11
	s_waitcnt lgkmcnt(0)
	v_mov_b32_e32 v4, 0
	global_load_dword v6, v4, s[12:13] sc1
	s_waitcnt vmcnt(0)
	v_cmp_eq_u32_e32 vcc, v6, v5
	s_and_saveexec_b64 s[10:11], vcc
	s_cbranch_execz .LBB0_831
	s_mov_b32 s25, 1
	s_mov_b64 s[14:15], 0
	s_branch .LBB0_822
